# NA: v_max3 tree, cross-lane max deferred to rare rescale path (no ds_bpermute round trips per chunk), Q fragment loads hoisted ahead of the K/V drain
# speedup vs baseline: 1.0692x; 1.0046x over previous
.LBB0_1385:
	s_ashr_i32 s0, s28, 7
	s_lshl_b32 s1, s28, 1
	s_bfe_u32 s7, s28, 0x30004
	s_and_b32 s6, s1, 30
	s_lshl_b32 s1, s0, 8
	v_mov_b32_e32 v2, v162
	s_add_i32 s1, s1, 0x8000
	s_lshl_b32 s8, s7, 7
	s_add_u32 s4, s31, s8
	v_lshlrev_b32_e32 v0, 4, v2
	s_addc_u32 s5, s33, 0
	v_and_b32_e32 v0, 0x70, v0
	v_ashrrev_i32_e32 v3, 3, v2
	v_lshl_add_u64 v[16:17], s[4:5], 0, v[0:1]
	s_add_u32 s4, s29, s8
	v_add_u32_e32 v4, s1, v3
	s_addc_u32 s5, s30, 0
	v_ashrrev_i32_e32 v5, 31, v4
	v_lshl_add_u64 v[20:21], s[4:5], 0, v[0:1]
	v_lshlrev_b64 v[4:5], 10, v[4:5]
	v_lshl_add_u64 v[6:7], v[16:17], 0, v[4:5]
	v_lshl_add_u64 v[4:5], v[20:21], 0, v[4:5]
	v_add_u32_e32 v28, 0x200, v2
	global_load_dwordx4 v[8:11], v[6:7], off
	global_load_dwordx4 v[12:15], v[4:5], off
	v_ashrrev_i32_e32 v4, 3, v28
	v_add_u32_e32 v6, s1, v4
	v_ashrrev_i32_e32 v7, 31, v6
	v_lshlrev_b64 v[6:7], 10, v[6:7]
	v_add_u32_e32 v32, 0x400, v2
	v_lshl_add_u64 v[22:23], v[16:17], 0, v[6:7]
	v_lshl_add_u64 v[6:7], v[20:21], 0, v[6:7]
	v_ashrrev_i32_e32 v5, 3, v32
	global_load_dwordx4 v[58:61], v[22:23], off
	global_load_dwordx4 v[62:65], v[6:7], off
	v_add_u32_e32 v6, s1, v5
	v_ashrrev_i32_e32 v7, 31, v6
	v_lshlrev_b64 v[6:7], 10, v[6:7]
	v_lshl_add_u64 v[22:23], v[16:17], 0, v[6:7]
	v_lshl_add_u64 v[6:7], v[20:21], 0, v[6:7]
	v_add_u32_e32 v33, 0x600, v2
	global_load_dwordx4 v[66:69], v[22:23], off
	global_load_dwordx4 v[70:73], v[6:7], off
	v_ashrrev_i32_e32 v6, 3, v33
	v_add_u32_e32 v22, s1, v6
	v_ashrrev_i32_e32 v23, 31, v22
	v_sub_u32_e64 v19, s6, 4 clamp
	v_lshlrev_b64 v[22:23], 10, v[22:23]
	s_ashr_i32 s1, s0, 31
	v_lshl_add_u64 v[24:25], v[16:17], 0, v[22:23]
	v_lshl_add_u64 v[22:23], v[20:21], 0, v[22:23]
	v_min_u32_e32 v7, 24, v19
	v_lshrrev_b32_e32 v19, 3, v2
	s_lshl_b64 s[0:1], s[0:1], 11
	global_load_dwordx4 v[74:77], v[24:25], off
	global_load_dwordx4 v[78:81], v[22:23], off
	v_and_or_b32 v22, v19, 63, s0
	v_ashrrev_i32_e32 v19, 9, v2
	v_add_lshl_u32 v24, v19, v7, 6
	v_ashrrev_i32_e32 v19, 9, v28
	v_mov_b32_e32 v23, s1
	v_ashrrev_i32_e32 v25, 31, v24
	v_add_lshl_u32 v28, v19, v7, 6
	v_lshl_add_u64 v[24:25], v[22:23], 0, v[24:25]
	v_ashrrev_i32_e32 v29, 31, v28
	v_lshlrev_b64 v[24:25], 10, v[24:25]
	v_lshl_add_u64 v[28:29], v[22:23], 0, v[28:29]
	v_lshl_add_u64 v[26:27], v[16:17], 0, v[24:25]
	v_lshlrev_b64 v[28:29], 10, v[28:29]
	v_ashrrev_i32_e32 v19, 9, v32
	v_lshl_add_u64 v[30:31], v[16:17], 0, v[28:29]
	global_load_dwordx4 v[82:85], v[26:27], off
	global_load_dwordx4 v[86:89], v[30:31], off
	v_add_lshl_u32 v26, v19, v7, 6
	v_ashrrev_i32_e32 v19, 9, v33
	v_ashrrev_i32_e32 v27, 31, v26
	v_add_lshl_u32 v32, v19, v7, 6
	v_lshl_add_u64 v[26:27], v[22:23], 0, v[26:27]
	v_ashrrev_i32_e32 v33, 31, v32
	v_lshlrev_b64 v[26:27], 10, v[26:27]
	v_lshl_add_u64 v[32:33], v[22:23], 0, v[32:33]
	v_lshl_add_u64 v[30:31], v[16:17], 0, v[26:27]
	v_lshlrev_b64 v[34:35], 10, v[32:33]
	v_add_u32_e32 v19, 0x800, v2
	v_lshl_add_u64 v[32:33], v[16:17], 0, v[34:35]
	global_load_dwordx4 v[90:93], v[30:31], off
	global_load_dwordx4 v[94:97], v[32:33], off
	v_ashrrev_i32_e32 v30, 9, v19
	v_add_u32_e32 v118, 0xa00, v2
	v_add_lshl_u32 v30, v30, v7, 6
	v_ashrrev_i32_e32 v32, 9, v118
	v_ashrrev_i32_e32 v31, 31, v30
	v_add_lshl_u32 v32, v32, v7, 6
	v_lshl_add_u64 v[30:31], v[22:23], 0, v[30:31]
	v_ashrrev_i32_e32 v33, 31, v32
	v_lshlrev_b64 v[36:37], 10, v[30:31]
	v_lshl_add_u64 v[32:33], v[22:23], 0, v[32:33]
	v_lshl_add_u64 v[30:31], v[16:17], 0, v[36:37]
	v_lshlrev_b64 v[42:43], 10, v[32:33]
	v_add_u32_e32 v119, 0xc00, v2
	v_lshl_add_u64 v[32:33], v[16:17], 0, v[42:43]
	global_load_dwordx4 v[98:101], v[30:31], off
	global_load_dwordx4 v[102:105], v[32:33], off
	v_ashrrev_i32_e32 v30, 9, v119
	v_add_u32_e32 v120, 0xe00, v2
	v_add_lshl_u32 v30, v30, v7, 6
	v_ashrrev_i32_e32 v32, 9, v120
	v_ashrrev_i32_e32 v31, 31, v30
	v_add_lshl_u32 v32, v32, v7, 6
	v_lshl_add_u64 v[30:31], v[22:23], 0, v[30:31]
	v_ashrrev_i32_e32 v33, 31, v32
	v_lshlrev_b64 v[44:45], 10, v[30:31]
	v_lshl_add_u64 v[32:33], v[22:23], 0, v[32:33]
	v_lshl_add_u64 v[30:31], v[16:17], 0, v[44:45]
	v_lshlrev_b64 v[50:51], 10, v[32:33]
	v_add_u32_e32 v122, 0x1000, v2
	v_lshl_add_u64 v[32:33], v[16:17], 0, v[50:51]
	global_load_dwordx4 v[106:109], v[30:31], off
	global_load_dwordx4 v[110:113], v[32:33], off
	v_ashrrev_i32_e32 v30, 9, v122
	v_add_lshl_u32 v30, v30, v7, 6
	v_ashrrev_i32_e32 v31, 31, v30
	v_lshl_add_u64 v[22:23], v[22:23], 0, v[30:31]
	v_lshlrev_b64 v[52:53], 10, v[22:23]
	v_lshl_add_u64 v[16:17], v[16:17], 0, v[52:53]
	v_lshl_add_u64 v[22:23], v[20:21], 0, v[24:25]
	global_load_dwordx4 v[114:117], v[16:17], off
	s_nop 0
	global_load_dwordx4 v[22:25], v[22:23], off
	v_lshl_add_u64 v[16:17], v[20:21], 0, v[28:29]
	v_lshl_add_u64 v[30:31], v[20:21], 0, v[26:27]
	global_load_dwordx4 v[26:29], v[16:17], off
	s_nop 0
	global_load_dwordx4 v[30:33], v[30:31], off
	v_lshl_add_u64 v[16:17], v[20:21], 0, v[34:35]
	v_lshl_add_u64 v[38:39], v[20:21], 0, v[36:37]
	global_load_dwordx4 v[34:37], v[16:17], off
	s_nop 0
	global_load_dwordx4 v[38:41], v[38:39], off
	v_lshl_add_u64 v[16:17], v[20:21], 0, v[42:43]
	v_lshl_add_u64 v[46:47], v[20:21], 0, v[44:45]
	global_load_dwordx4 v[42:45], v[16:17], off
	s_nop 0
	global_load_dwordx4 v[46:49], v[46:47], off
	v_lshl_add_u64 v[16:17], v[20:21], 0, v[50:51]
	v_lshl_add_u64 v[20:21], v[20:21], 0, v[52:53]
	global_load_dwordx4 v[50:53], v[16:17], off
	global_load_dwordx4 v[54:57], v[20:21], off
	v_or_b32_e32 v16, 0x14400, v0
	v_mul_lo_u32 v20, v3, s42
	v_or_b32_e32 v17, 0x1d400, v0
	v_add_u32_e32 v21, v16, v20
	s_waitcnt vmcnt(25)
	ds_write_b128 v21, v[8:11]
	v_add_u32_e32 v8, v17, v20
	s_waitcnt vmcnt(24)
	ds_write_b128 v8, v[12:15]
	v_mul_lo_u32 v8, v4, s42
	v_add_u32_e32 v9, v16, v8
	s_waitcnt vmcnt(23)
	ds_write_b128 v9, v[58:61]
	v_add_u32_e32 v9, v17, v8
	s_waitcnt vmcnt(22)
	ds_write_b128 v9, v[62:65]
	v_ashrrev_i32_e32 v211, 8, v2
	v_lshrrev_b32_e32 v210, 2, v2
	v_add_u32_e32 v211, s6, v211
	v_and_b32_e32 v212, 48, v210
	v_lshlrev_b32_e32 v210, 6, v211
	v_and_b32_e32 v213, 15, v2
	v_ashrrev_i32_e32 v211, 31, v210
	v_lshl_add_u64 v[210:211], s[0:1], 0, v[210:211]
	v_or_b32_e32 v212, v212, v213
	v_or_b32_e32 v210, v212, v210
	s_lshl_b32 s98, s7, 7
	s_mov_b32 s99, 0
	v_lshlrev_b64 v[210:211], 10, v[210:211]
	v_bfe_u32 v212, v2, 4, 2
	v_lshl_add_u64 v[210:211], s[64:65], 0, v[210:211]
	v_lshlrev_b32_e32 v212, 4, v212
	v_mov_b32_e32 v213, 0
	v_lshl_add_u64 v[210:211], v[210:211], 0, s[98:99]
	v_lshl_add_u64 v[210:211], v[210:211], 0, v[212:213]
	global_load_dwordx4 v[58:61], v[210:211], off
	global_load_dwordx4 v[62:65], v[210:211], off offset:64
	v_mul_lo_u32 v9, v5, s42
	v_add_u32_e32 v10, v16, v9
	s_waitcnt vmcnt(21)
	ds_write_b128 v10, v[66:69]
	v_add_u32_e32 v10, v17, v9
	s_waitcnt vmcnt(20)
	ds_write_b128 v10, v[70:73]
	v_mul_lo_u32 v10, v6, s42
	v_add_u32_e32 v11, v16, v10
	s_waitcnt vmcnt(19)
	ds_write_b128 v11, v[74:77]
	v_add_u32_e32 v11, v17, v10
	s_waitcnt vmcnt(18)
	ds_write_b128 v11, v[78:81]
	v_add_u32_e32 v11, v0, v20
	v_add_u32_e32 v8, v0, v8
	s_waitcnt vmcnt(17)
	ds_write_b128 v11, v[82:85]
	s_waitcnt vmcnt(16)
	ds_write_b128 v8, v[86:89]
	v_add_u32_e32 v8, v0, v9
	v_ashrrev_i32_e32 v12, 3, v19
	s_waitcnt vmcnt(15)
	ds_write_b128 v8, v[90:93]
	v_add_u32_e32 v8, v0, v10
	s_waitcnt vmcnt(14)
	ds_write_b128 v8, v[94:97]
	v_mad_u64_u32 v[8:9], s[4:5], v12, s42, v[0:1]
	v_ashrrev_i32_e32 v11, 3, v118
	v_ashrrev_i32_e32 v10, 3, v119
	v_cmp_gt_i32_e32 vcc, s43, v2
	s_waitcnt vmcnt(13)
	ds_write_b128 v8, v[98:101]
	v_mad_u64_u32 v[8:9], s[4:5], v11, s42, v[0:1]
	s_waitcnt vmcnt(12)
	ds_write_b128 v8, v[102:105]
	v_mad_u64_u32 v[8:9], s[4:5], v10, s42, v[0:1]
	v_ashrrev_i32_e32 v9, 3, v120
	v_mad_u64_u32 v[14:15], s[4:5], v9, s42, v[0:1]
	s_waitcnt vmcnt(11)
	ds_write_b128 v8, v[106:109]
	v_ashrrev_i32_e32 v8, 3, v122
	s_waitcnt vmcnt(10)
	ds_write_b128 v14, v[110:113]
	v_mad_u64_u32 v[14:15], s[4:5], v8, s42, v[0:1]
	s_waitcnt vmcnt(9)
	ds_write_b128 v14, v[114:117]
	s_and_saveexec_b64 s[4:5], vcc
	s_cbranch_execz .LBB0_1387
	s_mul_i32 s8, s7, 0x1d1
	v_add_u32_e32 v14, s8, v2
	v_readlane_b32 s68, v247, 33
	v_ashrrev_i32_e32 v15, 31, v14
	v_readlane_b32 s69, v247, 34
	v_lshl_add_u32 v13, v2, 2, v121
	v_readlane_b32 s70, v247, 35
	v_lshl_add_u64 v[14:15], v[14:15], 2, s[68:69]
	global_load_dword v0, v[14:15], off
	v_readlane_b32 s71, v247, 36
	v_readlane_b32 s72, v247, 37
	v_readlane_b32 s73, v247, 38
	v_readlane_b32 s74, v247, 39
	v_readlane_b32 s75, v247, 40
	v_readlane_b32 s76, v247, 41
	v_readlane_b32 s77, v247, 42
	v_readlane_b32 s78, v247, 43
	v_readlane_b32 s79, v247, 44
	v_readlane_b32 s80, v247, 45
	v_readlane_b32 s81, v247, 46
	v_readlane_b32 s82, v247, 47
	v_readlane_b32 s83, v247, 48
	s_waitcnt vmcnt(0)
	v_mul_f32_e32 v0, 0x3fb8aa3b, v0
	ds_write_b32 v13, v0
.LBB0_1387:
	s_or_b64 exec, exec, s[4:5]
	v_lshrrev_b32_e32 v14, 2, v2
	v_ashrrev_i32_e32 v17, 8, v2
	v_and_b32_e32 v20, 48, v14
	v_add_u32_e32 v19, s6, v17
	v_sub_u32_e64 v14, v20, 8 clamp
	v_min_u32_e32 v140, 32, v14
	v_lshlrev_b32_e32 v14, 6, v19
	s_and_b32 s36, s34, 30
	v_and_b32_e32 v139, 15, v2
	v_ashrrev_i32_e32 v15, 31, v14
	v_sub_u32_e64 v0, s36, 4 clamp
	v_lshl_add_u64 v[14:15], s[0:1], 0, v[14:15]
	v_or_b32_e32 v20, v20, v139
	v_min_u32_e32 v0, 24, v0
	v_or_b32_e32 v14, v20, v14
	s_lshl_b32 s4, s7, 6
	v_lshlrev_b32_e32 v13, 13, v0
	v_max_i32_e32 v0, 4, v19
	v_lshlrev_b64 v[118:119], 9, v[14:15]
	v_lshlrev_b64 v[14:15], 10, v[14:15]
	v_add_u32_e32 v0, -4, v0
	v_bfe_u32 v98, v2, 4, 2
	v_lshl_add_u64 v[14:15], s[64:65], 0, v[14:15]
	s_lshl_b32 s26, s4, 1
	v_min_u32_e32 v21, 24, v0
	v_lshl_add_u64 v[14:15], v[14:15], 0, s[26:27]
	v_lshlrev_b32_e32 v0, 4, v98
	v_lshl_add_u64 v[14:15], v[14:15], 0, v[0:1]
	v_sub_u32_e64 v14, v20, 8 clamp
	v_lshlrev_b32_e32 v141, 2, v98
	v_min_u32_e32 v14, 48, v14
	v_add_u32_e32 v15, v140, v141
	v_add_u32_e32 v66, 16, v14
	v_sub_u32_e32 v67, v15, v20
	v_cmp_ge_u32_e32 vcc, v15, v14
	v_cmp_lt_u32_e64 s[0:1], v15, v66
	v_med3_i32 v142, v67, -15, 15
	v_or_b32_e32 v67, 1, v15
	s_and_b64 s[4:5], vcc, s[0:1]
	v_cmp_ge_u32_e32 vcc, v67, v14
	v_cmp_lt_u32_e64 s[0:1], v67, v66
	v_sub_u32_e32 v67, v67, v20
	v_med3_i32 v143, v67, -15, 15
	v_or_b32_e32 v67, 2, v15
	s_and_b64 s[6:7], vcc, s[0:1]
	v_cmp_ge_u32_e32 vcc, v67, v14
	v_cmp_lt_u32_e64 s[0:1], v67, v66
	v_sub_u32_e32 v67, v67, v20
	v_med3_i32 v144, v67, -15, 15
	v_or_b32_e32 v67, 3, v15
	s_and_b64 s[8:9], vcc, s[0:1]
	v_cmp_ge_u32_e32 vcc, v67, v14
	v_cmp_lt_u32_e64 s[0:1], v67, v66
	v_sub_u32_e32 v67, v67, v20
	v_med3_i32 v145, v67, -15, 15
	v_add_u32_e32 v67, 16, v15
	s_and_b64 s[10:11], vcc, s[0:1]
	v_cmp_ge_u32_e32 vcc, v67, v14
	v_sub_u32_e32 v67, v67, v20
	v_cmp_lt_u32_e64 s[0:1], v15, v14
	v_med3_i32 v146, v67, -15, 15
	v_add_u32_e32 v67, 17, v15
	s_and_b64 s[12:13], vcc, s[0:1]
	v_cmp_ge_u32_e32 vcc, v67, v14
	v_cmp_lt_u32_e64 s[0:1], v67, v66
	v_sub_u32_e32 v67, v67, v20
	v_med3_i32 v147, v67, -15, 15
	v_add_u32_e32 v67, 18, v15
	s_and_b64 s[14:15], vcc, s[0:1]
	v_cmp_ge_u32_e32 vcc, v67, v14
	v_cmp_lt_u32_e64 s[0:1], v67, v66
	v_add_u32_e32 v15, 19, v15
	s_and_b64 s[16:17], vcc, s[0:1]
	v_cmp_ge_u32_e32 vcc, v15, v14
	v_cmp_lt_u32_e64 s[0:1], v15, v66
	v_or_b32_e32 v120, 0x1d400, v0
	v_sub_u32_e32 v67, v67, v20
	s_and_b64 s[18:19], vcc, s[0:1]
	v_mad_u32_u24 v0, v139, s42, v120
	v_cmp_lt_i32_e32 vcc, v135, v136
	v_med3_i32 v148, v67, -15, 15
	s_waitcnt lgkmcnt(0)
	s_barrier
	ds_read_b128 v[66:69], v0
	ds_read_b128 v[70:73], v0 offset:64
	ds_read_b128 v[74:77], v0 offset:2304
	ds_read_b128 v[78:81], v0 offset:2368
	ds_read_b128 v[82:85], v0 offset:4608
	ds_read_b128 v[86:89], v0 offset:4672
	ds_read_b128 v[90:93], v0 offset:6912
	ds_read_b128 v[94:97], v0 offset:6976
	v_cndmask_b32_e32 v0, v134, v135, vcc
	v_cmp_lt_i32_e32 vcc, v137, v136
	v_lshlrev_b32_e32 v150, 2, v0
	v_sub_u32_e32 v153, v21, v7
	v_cndmask_b32_e32 v0, v134, v137, vcc
	v_lshlrev_b32_e32 v151, 2, v0
	v_bfe_u32 v0, v2, 2, 2
	v_or_b32_e32 v0, v141, v0
	v_mul_u32_u24_e32 v152, 0x90, v0
	v_lshlrev_b32_e32 v0, 2, v2
	v_sub_u32_e32 v14, v15, v20
	v_and_b32_e32 v20, 12, v0
	v_lshl_or_b32 v0, v153, 6, v140
	v_add_lshl_u32 v0, v0, v139, 7
	v_add_u32_e32 v154, 0x14400, v0
	v_add_u32_e32 v157, 0x14c00, v0
	v_add_u32_e32 v158, 0x16400, v0
	v_add_u32_e32 v159, 0x16c00, v0
	v_xor_b32_e32 v0, v3, v2
	v_lshlrev_b32_e32 v0, 4, v0
	v_and_b32_e32 v0, 0x70, v0
	v_lshl_or_b32 v0, v3, 7, v0
	v_add_u32_e32 v161, 0x14400, v0
	v_xor_b32_e32 v0, v4, v2
	v_lshlrev_b32_e32 v0, 4, v0
	v_and_b32_e32 v0, 0x70, v0
	v_lshl_or_b32 v0, v4, 7, v0
	v_add_u32_e32 v164, 0x14400, v0
	v_xor_b32_e32 v0, v5, v2
	v_lshlrev_b32_e32 v0, 4, v0
	v_and_b32_e32 v0, 0x70, v0
	v_lshl_or_b32 v0, v5, 7, v0
	v_add_u32_e32 v165, 0x14400, v0
	v_xor_b32_e32 v0, v6, v2
	v_lshlrev_b32_e32 v0, 4, v0
	v_and_b32_e32 v0, 0x70, v0
	v_lshl_or_b32 v0, v6, 7, v0
	v_add_u32_e32 v166, 0x14400, v0
	v_xor_b32_e32 v0, v12, v2
	v_lshlrev_b32_e32 v0, 4, v0
	v_and_b32_e32 v0, 0x70, v0
	v_lshl_or_b32 v0, v12, 7, v0
	v_add_u32_e32 v167, 0x14400, v0
	v_xor_b32_e32 v0, v11, v2
	v_lshlrev_b32_e32 v0, 4, v0
	v_and_b32_e32 v0, 0x70, v0
	v_lshl_or_b32 v0, v11, 7, v0
	v_add_u32_e32 v168, 0x14400, v0
	v_xor_b32_e32 v0, v10, v2
	v_lshlrev_b32_e32 v0, 4, v0
	v_and_b32_e32 v0, 0x70, v0
	v_lshl_or_b32 v0, v10, 7, v0
	v_add_u32_e32 v169, 0x14400, v0
	v_xor_b32_e32 v0, v9, v2
	v_lshlrev_b32_e32 v0, 4, v0
	v_and_b32_e32 v0, 0x70, v0
	v_lshl_or_b32 v0, v9, 7, v0
	v_add_u32_e32 v170, 0x14400, v0
	v_xor_b32_e32 v0, v8, v2
	v_lshlrev_b32_e32 v0, 4, v0
	v_and_b32_e32 v0, 0x70, v0
	v_lshl_or_b32 v0, v8, 7, v0
	v_add_u32_e32 v171, 0x14400, v0
	v_add_u32_e32 v0, s36, v17
	v_max_i32_e32 v0, 4, v0
	v_lshrrev_b32_e32 v16, 4, v2
	v_and_b32_e32 v7, 7, v2
	v_add_u32_e32 v0, -4, v0
	v_med3_i32 v149, v14, -15, 15
	v_bitop3_b32 v14, v16, v7, 3 bitop3:0x6c
	v_bitop3_b32 v7, v98, v7, 4 bitop3:0x36
	v_min_u32_e32 v0, 24, v0
	v_add_lshl_u32 v2, v140, v139, 7
	v_lshlrev_b32_e32 v155, 4, v14
	v_lshlrev_b32_e32 v156, 4, v7
	v_lshl_add_u32 v0, v0, 13, v2
	v_or_b32_e32 v2, v0, v156
	v_or_b32_e32 v0, v0, v155
	v_sub_u32_e32 v173, v2, v13
	v_sub_u32_e32 v174, v0, v13
	v_mov_b32_e32 v2, v1
	v_mov_b32_e32 v3, v1
	v_mov_b32_e32 v4, v1
	v_mov_b32_e32 v5, v1
	v_mov_b32_e32 v6, v1
	v_mov_b32_e32 v7, v1
	v_mov_b32_e32 v8, v1
	v_mov_b32_e32 v9, v1
	v_mov_b32_e32 v10, v1
	v_mov_b32_e32 v11, v1
	v_mov_b32_e32 v12, v1
	v_mov_b32_e32 v13, v1
	v_mov_b32_e32 v14, v1
	v_mov_b32_e32 v15, v1
	v_mov_b32_e32 v0, v1
	v_mov_b64_e32 v[16:17], v[14:15]
	s_mov_b32 s28, 0
	v_sub_u32_e32 v160, v21, v19
	v_or_b32_e32 v172, 64, v140
	v_mov_b32_e32 v98, v1
	v_mov_b32_e32 v99, v1
	v_mov_b32_e32 v100, v1
	v_mov_b32_e32 v101, v1
	v_mov_b32_e32 v175, 0
	s_mov_b32 s49, 0x15600
	v_lshlrev_b32_e32 v176, 1, v20
	s_mov_b32 s50, 0
	v_mov_b64_e32 v[14:15], v[12:13]
	v_mov_b64_e32 v[12:13], v[10:11]
	v_mov_b64_e32 v[10:11], v[8:9]
	v_mov_b64_e32 v[8:9], v[6:7]
	v_mov_b64_e32 v[6:7], v[4:5]
	v_mov_b64_e32 v[4:5], v[2:3]
	v_mov_b64_e32 v[2:3], v[0:1]
	s_branch .LBB0_1389

.LBB0_1402:
	v_max3_f32 v19, v0, v111, v112
	v_max3_f32 v20, v113, v114, v115
	v_max3_f32 v19, v19, v116, v117
	v_max3_f32 v20, v20, v102, v103
	v_max3_f32 v21, v104, v105, v106
	v_max3_f32 v21, v21, v107, v108
	v_max3_f32 v19, v19, v20, v109
	v_max_f32_e32 v19, v19, v21
	s_cmp_eq_u32 s28, 0
	s_cselect_b64 s[0:1], -1, 0
	v_cmp_lt_f32_e32 vcc, s47, v19
	s_or_b64 vcc, s[0:1], vcc
	s_cbranch_vccz .LBB0_1404
	v_mov_b32_e32 v20, v19
	s_nop 1
	v_permlane16_swap_b32_e32 v19, v20
	v_max_f32_e32 v19, v19, v20
	v_mov_b32_e32 v20, v19
	s_nop 1
	v_permlane32_swap_b32_e32 v19, v20
	v_max_f32_e32 v19, v19, v20
	v_max_f32_e32 v20, v19, v19
	v_max_f32_e32 v20, 0, v20
	v_cndmask_b32_e64 v19, v20, v19, s[0:1]
	v_exp_f32_e64 v20, -v19
	v_sub_f32_e32 v0, v0, v19
	v_sub_f32_e32 v111, v111, v19
	v_sub_f32_e32 v112, v112, v19
	v_sub_f32_e32 v113, v113, v19
	v_sub_f32_e32 v114, v114, v19
	v_sub_f32_e32 v115, v115, v19
	v_sub_f32_e32 v116, v116, v19
	v_sub_f32_e32 v117, v117, v19
	v_sub_f32_e32 v102, v102, v19
	v_sub_f32_e32 v103, v103, v19
	v_sub_f32_e32 v104, v104, v19
	v_sub_f32_e32 v105, v105, v19
	v_sub_f32_e32 v106, v106, v19
	v_sub_f32_e32 v107, v107, v19
	v_sub_f32_e32 v108, v108, v19
	v_sub_f32_e32 v109, v109, v19
	v_pk_mul_f32 v[16:17], v[16:17], v[20:21] op_sel_hi:[1,0]
	v_pk_mul_f32 v[14:15], v[14:15], v[20:21] op_sel_hi:[1,0]
	v_pk_mul_f32 v[12:13], v[12:13], v[20:21] op_sel_hi:[1,0]
	v_pk_mul_f32 v[10:11], v[10:11], v[20:21] op_sel_hi:[1,0]
	v_pk_mul_f32 v[8:9], v[8:9], v[20:21] op_sel_hi:[1,0]
	v_pk_mul_f32 v[6:7], v[6:7], v[20:21] op_sel_hi:[1,0]
	v_pk_mul_f32 v[4:5], v[4:5], v[20:21] op_sel_hi:[1,0]
	v_pk_mul_f32 v[2:3], v[2:3], v[20:21] op_sel_hi:[1,0]
	v_add_f32_e32 v175, v175, v19
	v_pk_mul_f32 v[100:101], v[100:101], v[20:21] op_sel_hi:[1,0]
	v_pk_mul_f32 v[98:99], v[98:99], v[20:21] op_sel_hi:[1,0]
